# attn queue order: items size-descending across the four (b,h) streams of an XCD queue (pp = it>>2, stream = it&3)
# speedup vs baseline: 1.0102x; 1.0063x over previous
; __global__ void __launch_bounds__(512, 2) hybrid_fwd(Ctx c) {
;     ...
;                 __syncthreads();
;                 const int it = (int)MISC[16];
;                 __syncthreads();
;                 if (it >= 128) break;
;                 const int bh = 4 * xq + (it >> 5), pp = it & 31;
.LBB0_821:
	s_or_b64 exec, exec, s[0:1]
	s_waitcnt lgkmcnt(0)
	s_barrier
	ds_read_b32 v0, v204
	s_movk_i32 s0, 0x7f
	s_waitcnt lgkmcnt(0)
	s_barrier
	v_cmp_lt_i32_e32 vcc, s0, v0
	v_readfirstlane_b32 s45, v0
	s_mov_b64 s[0:1], -1
	s_cbranch_vccnz .LBB0_816
	s_mov_b32 s0, -1
	s_and_b32 s50, s45, 3
	v_mbcnt_lo_u32_b32 v0, s0, 0
	v_mbcnt_hi_u32_b32 v0, s0, v0
	s_add_i32 s44, s50, s79
	s_waitcnt vmcnt(3)
	v_add_u32_e32 v44, s33, v0
	s_and_b32 s80, s44, 7
	s_nop 0
	v_readfirstlane_b32 s51, v44
	v_cmp_gt_i32_e32 vcc, s66, v44
	s_and_saveexec_b64 s[0:1], vcc
	s_cbranch_execz .LBB0_832
	v_add_u32_e32 v0, 0xffffff80, v44
	v_sub_u32_e32 v2, 0x80, v44
	v_max_i32_e32 v0, v0, v2
	v_cmp_lt_u32_e32 vcc, 7, v0
	s_and_saveexec_b64 s[2:3], vcc
	s_cbranch_execz .LBB0_831
	v_cmp_lt_u32_e32 vcc, 11, v0
	v_mov_b32_e32 v2, 8
	s_and_saveexec_b64 s[16:17], vcc
	s_cbranch_execz .LBB0_830
	v_cmp_lt_u32_e32 vcc, 15, v0
	v_mov_b32_e32 v2, 9
	s_and_saveexec_b64 s[40:41], vcc
	s_cbranch_execz .LBB0_829
	v_cmp_lt_u32_e32 vcc, 22, v0
	v_mov_b32_e32 v2, 10
	s_and_saveexec_b64 s[42:43], vcc
	v_cmp_gt_u32_e32 vcc, s68, v0
	s_nop 1
	v_cndmask_b32_e64 v2, 15, 14, vcc
	v_cmp_lt_u32_e32 vcc, 63, v0
	s_nop 1
	v_cndmask_b32_e32 v2, 13, v2, vcc
	v_cmp_lt_u32_e32 vcc, 45, v0
	s_nop 1
	v_cndmask_b32_e32 v2, 12, v2, vcc
	v_cmp_lt_u32_e32 vcc, 31, v0
	s_nop 1
	v_cndmask_b32_e32 v2, 11, v2, vcc
	s_or_b64 exec, exec, s[42:43]

; template <bool SAMPLE> __device__ __forceinline__ void attn_unit16(const Ctx& c, LAS unsigned char* lds, int b, int h, int qb, int wave_s) {
;     ...
;     for (int qt = 0; qt < NQT; ++qt) { const size_t qrow = SAMPLE ? (size_t)ROW_S0 + b * 16 + c16 : (size_t)b * SEQ + tq0 + 16 * qt + c16;
;         const bf16* Q = (const bf16*)(ws + WS_DQ) + qrow * D + h * 128 + mp * 64 + q4 * 8;
;         qr[qt][0] = *(const bf16x8*)Q; qr[qt][1] = *(const bf16x8*)(Q + 32); }
;     const int lrow = tid >> 3, lck = tid & 7;
;     u32x4 kreg[2], vreg[2];
;     f32x4 kraw[4], vraw[4]; bool kok = true, vok = true;
;     auto load_kv = [&](int j, bool isk) {
;         u32x4 r0, r1;
;         if (SAMPLE) {
;             const float* p; bool ok = true;
;             if (j < 16) { const size_t rr = ((size_t)b * PAST + 64 * j + lrow) * 8 + h; p = (isk ? c.cache_k : c.cache_v) + rr * 128; }
;             else { ok = lrow < 16; const size_t rr = ((size_t)b * 16 + (lrow & 15)) * 8 + h; p = c.out + (isk ? O_KS : O_VS) + rr * 128; }
;             if (isk) { kraw[0] = __builtin_nontemporal_load((const f32x4*)(p + lck * 8)); kraw[1] = __builtin_nontemporal_load((const f32x4*)(p + lck * 8 + 4)); kraw[2] = __builtin_nontemporal_load((const f32x4*)(p + 64 + lck * 8)); kraw[3] = __builtin_nontemporal_load((const f32x4*)(p + 64 + lck * 8 + 4)); kok = ok; }
;             else     { vraw[0] = __builtin_nontemporal_load((const f32x4*)(p + lck * 8)); vraw[1] = __builtin_nontemporal_load((const f32x4*)(p + lck * 8 + 4)); vraw[2] = __builtin_nontemporal_load((const f32x4*)(p + 64 + lck * 8)); vraw[3] = __builtin_nontemporal_load((const f32x4*)(p + 64 + lck * 8 + 4)); vok = ok; }
;             return;
;         }
;         if (!SAMPLE) {
;             const int kidx0 = j == 0 ? 0 : 16 + 64 * (j - 1);
;             const size_t rr = (size_t)(b * 8 + h) * KROWS + kidx0 + lrow;
;             const bf16* p = (const bf16*)(ws + (isk ? WS_DK : WS_DV)) + rr * 128;
;             r0 = *(const u32x4*)(p + lck * 8); r1 = *(const u32x4*)(p + 64 + lck * 8);
;         } else {
;             const float* p; bool ok = true;
;             if (j < 16) { const size_t rr = ((size_t)b * PAST + 64 * j + lrow) * 8 + h; p = (isk ? c.cache_k : c.cache_v) + rr * 128; }
;             else { ok = lrow < 16; const size_t rr = ((size_t)b * 16 + (lrow & 15)) * 8 + h; p = c.out + (isk ? O_KS : O_VS) + rr * 128; }
.LBB0_832:
	s_or_b64 exec, exec, s[0:1]
	s_lshr_b32 s56, s45, 2
	s_bfe_u32 s0, s51, 0x20007
	s_ashr_i32 s16, s44, 3
	s_xor_b32 s2, s56, 63
	s_xor_b32 s63, s0, 2
	s_lshl_b32 s0, s2, 7
	s_lshl_b32 s1, s63, 5
	s_ashr_i32 s17, s16, 31
	s_or_b32 s86, s1, s0
	s_lshl_b64 s[16:17], s[16:17], 13
	s_bfe_u32 s81, s51, 0x10006
	s_or_b32 s62, s16, s86
	s_lshl_b32 s3, s80, 8
	s_add_u32 s40, s92, s3
	s_addc_u32 s41, s93, 0
	s_lshl_b32 s3, s81, 7
	v_bfe_u32 v210, v44, 4, 2
	s_add_u32 s42, s40, s3
	v_ashrrev_i32_e32 v2, 3, v44
	s_addc_u32 s43, s41, 0
	v_lshlrev_b32_e32 v0, 4, v210
	v_ashrrev_i32_e32 v3, 31, v2
	v_lshl_add_u64 v[20:21], s[42:43], 0, v[0:1]
	v_mad_i64_i32 v[4:5], s[42:43], s44, v207, v[2:3]
	v_lshlrev_b64 v[4:5], 8, v[4:5]
	v_lshlrev_b32_e32 v10, 4, v44
	v_lshl_add_u64 v[6:7], s[4:5], 0, v[4:5]
	s_waitcnt vmcnt(2)
	v_and_b32_e32 v46, 0x70, v10
	v_mov_b32_e32 v47, v1
	v_lshl_add_u64 v[10:11], v[6:7], 0, v[46:47]
	v_and_b32_e32 v45, 15, v44
	global_load_dwordx4 v[36:39], v[10:11], off
	global_load_dwordx4 v[40:43], v[10:11], off offset:128
	v_lshl_add_u64 v[4:5], s[6:7], 0, v[4:5]
	v_add_co_u32_e32 v10, vcc, s69, v10
	v_or_b32_e32 v8, s62, v45
	v_mov_b32_e32 v9, s17
	v_lshl_add_u64 v[12:13], v[4:5], 0, v[46:47]
	v_addc_co_u32_e32 v11, vcc, 0, v11, vcc
	global_load_dwordx4 v[4:7], v[12:13], off
	s_nop 0
	global_load_dwordx4 v[12:15], v[12:13], off offset:128
	s_nop 0
	global_load_dwordx4 v[28:31], v[10:11], off
	global_load_dwordx4 v[32:35], v[10:11], off offset:128
	v_lshlrev_b64 v[22:23], 11, v[8:9]
	v_lshl_add_u64 v[16:17], v[20:21], 0, v[22:23]
	v_or_b32_e32 v22, 0x8000, v22
	v_lshl_add_u64 v[24:25], v[20:21], 0, v[22:23]
	global_load_dwordx4 v[8:11], v[16:17], off
	s_nop 0
	global_load_dwordx4 v[16:19], v[16:17], off offset:64
	s_nop 0
	global_load_dwordx4 v[20:23], v[24:25], off
	s_nop 0
	global_load_dwordx4 v[24:27], v[24:25], off offset:64
	v_mul_lo_u32 v47, v2, s70
	v_lshlrev_b32_e32 v48, 4, v2
	v_add_u32_e32 v47, 0, v47
	v_add_u32_e32 v211, v47, v46
	v_add_u32_e32 v47, v47, v48
	s_add_i32 s3, s3, 0
	v_add_u32_e32 v213, v47, v46
	s_waitcnt vmcnt(9)
	ds_write_b128 v211, v[36:39]
	s_waitcnt vmcnt(8)
	ds_write_b128 v211, v[40:43] offset:128
	s_waitcnt vmcnt(7)
	ds_write_b128 v213, v[4:7] offset:17408
	s_waitcnt vmcnt(6)
	ds_write_b128 v213, v[12:15] offset:17536
	s_waitcnt vmcnt(5)
	ds_write_b128 v211, v[28:31] offset:35840
	s_waitcnt vmcnt(4)
	ds_write_b128 v211, v[32:35] offset:35968
	v_mov_b32_e32 v36, s3
	v_mad_u32_u24 v36, v45, s70, v36
	v_add_u32_e32 v214, v36, v0
	s_waitcnt lgkmcnt(0)
	s_barrier
	ds_read_b128 v[36:39], v214
	ds_read_b128 v[40:43], v214 offset:64
	s_waitcnt vmcnt(3) lgkmcnt(1)
	v_mfma_f32_16x16x32_bf16 v[46:49], v[36:39], v[8:11], 0
	s_waitcnt vmcnt(1)
	v_mfma_f32_16x16x32_bf16 v[36:39], v[36:39], v[20:23], 0
	s_waitcnt lgkmcnt(0)
	v_mfma_f32_16x16x32_bf16 v[48:51], v[40:43], v[16:19], v[46:49]
	s_waitcnt vmcnt(0)
	v_mfma_f32_16x16x32_bf16 v[52:55], v[40:43], v[24:27], v[36:39]
	v_mov_b32_e32 v0, s71
	ds_read_b32 v0, v0
	v_mov_b32_e32 v46, 0xff800000
	s_waitcnt lgkmcnt(0)
	s_nop 1
	v_pk_add_f32 v[42:43], v[48:49], v[0:1] op_sel_hi:[1,0]
	v_pk_add_f32 v[40:41], v[50:51], v[0:1] op_sel_hi:[1,0]
	v_pk_add_f32 v[38:39], v[52:53], v[0:1] op_sel_hi:[1,0]
	v_pk_add_f32 v[36:37], v[54:55], v[0:1] op_sel_hi:[1,0]
	v_max3_f32 v0, v42, v43, v40
	v_max_f32_e32 v47, 0xff800000, v41
	v_max3_f32 v47, v0, v46, v47
	v_max3_f32 v0, v38, v39, v36
	v_max_f32_e32 v48, 0xff800000, v37
	v_max3_f32 v0, v0, v46, v48
	v_max_f32_e64 v48, |v47|, |v0|
	v_cmp_lt_f32_e32 vcc, s72, v48
	s_cbranch_vccz .LBB0_834
	v_and_b32_e32 v48, 64, v212
	v_xor_b32_e32 v46, 16, v212
	v_add_u32_e32 v48, 64, v48
	v_cmp_lt_i32_e32 vcc, v46, v48
	v_xor_b32_e32 v49, 32, v212
	s_nop 0
	v_cndmask_b32_e32 v46, v212, v46, vcc
	v_lshlrev_b32_e32 v46, 2, v46
	ds_bpermute_b32 v50, v46, v47
	ds_bpermute_b32 v46, v46, v0
	v_cmp_lt_i32_e32 vcc, v49, v48
	v_max_f32_e32 v0, v0, v0
	v_max_f32_e32 v47, v47, v47
	v_cndmask_b32_e32 v48, v212, v49, vcc
	s_waitcnt lgkmcnt(0)
	v_max_f32_e32 v46, v46, v46
	v_lshlrev_b32_e32 v48, 2, v48
	v_max_f32_e32 v49, v50, v50
	v_max_f32_e32 v0, v0, v46
	v_max_f32_e32 v47, v47, v49
	ds_bpermute_b32 v46, v48, v0
	ds_bpermute_b32 v49, v48, v47
	s_waitcnt lgkmcnt(1)
	v_max_f32_e32 v46, v46, v46
	s_waitcnt lgkmcnt(0)
	v_max_f32_e32 v48, v49, v49
	v_max_f32_e32 v0, v0, v46
	v_max_f32_e32 v47, v47, v48
	v_cmp_gt_f32_e64 vcc, |v0|, s72
	s_nop 1
	v_cndmask_b32_e32 v197, 0, v0, vcc
	v_cmp_gt_f32_e64 vcc, |v47|, s72
	v_exp_f32_e64 v201, -v197
	v_sub_f32_e32 v0, 0xff800000, v197
	v_cndmask_b32_e32 v196, 0, v47, vcc
	v_exp_f32_e64 v200, -v196
	v_sub_f32_e32 v42, v42, v196
	v_sub_f32_e32 v43, v43, v196
	v_sub_f32_e32 v40, v40, v196
	v_sub_f32_e32 v41, v41, v196
	v_sub_f32_e32 v46, 0xff800000, v196
	v_sub_f32_e32 v38, v38, v197
	v_sub_f32_e32 v39, v39, v197
	v_sub_f32_e32 v36, v36, v197
	v_sub_f32_e32 v37, v37, v197
	v_mov_b32_e32 v47, v0
	v_mov_b32_e32 v48, v0
	v_mov_b32_e32 v49, v0
	s_branch .LBB0_835
